# cross-lane sums without LDS round trips: bprep butterfly via DPP row ops + v_permlane16_swap, EpiResid epilogue ssq lane^16/lane^32 via v_permlane16/32_swap
# speedup vs baseline: 1.0029x; 1.0029x over previous
; DI float bflo(unsigned u) { return __uint_as_float(u << 16); }
; DI float bfhi(unsigned u) { return __uint_as_float(u & 0xffff0000u); }
; DI unsigned pack2(float lo, float hi) { f32x2_t v = {lo, hi}; return __builtin_bit_cast(unsigned, __builtin_convertvector(v, bf16x2_t)); }
; DI void bprep_phase(const Params& p) {
;     ...
;   for (int t = blockIdx.x * 16 + tl; t < NTOK; t += gridDim.x * 16) {
;     const int pos = (t < PROMPT_T) ? t : ((t - PROMPT_T) & (SAMPLE_T - 1));
;     const float ang = (float)((pi < 16) ? (pos >> 6) : (pos & 63)) * fr;
;     const float cs = __cosf(ang), sn = __sinf(ang);
;     unsigned* rowp = (unsigned*)(p.big + (size_t)t * 2304);
; #pragma unroll
;     for (int hd = 0; hd < 10; ++hd) {
;       const int col = (hd < 8) ? (1536 + hd * 64) : (2048 + (hd - 8) * 64);
;       unsigned u = rowp[(col >> 1) + pi];
;       float x1 = bflo(u), x2 = bfhi(u);
;       float ss = x1 * x1 + x2 * x2;
; #pragma unroll
;       for (int o = 16; o > 0; o >>= 1) ss += __shfl_xor(ss, o);
;       const float r = rsqrtf(ss * (1.0f / 64.0f) + EPS);
;       x1 = x1 * r * ((hd < 8) ? qg0 : kg0); x2 = x2 * r * ((hd < 8) ? qg1 : kg1);
;       const float qs = (hd < 8) ? 0.125f * LOG2E : 1.f;
;       rowp[(col >> 1) + pi] = pack2((x1 * cs - x2 * sn) * qs, (x1 * sn + x2 * cs) * qs);
;     }
;   }
.LBB0_249:
	s_movk_i32 s0, 0x4000
	v_cmp_gt_i32_e64 s[0:1], s0, v9
	v_and_b32_e32 v0, 0xfff, v9
	s_nop 0
	v_cndmask_b32_e64 v0, v0, v9, s[0:1]
	v_mad_i64_i32 v[10:11], s[0:1], v9, s24, v[6:7]
	global_load_dword v30, v[10:11], off offset:3072
	global_load_dword v31, v[10:11], off offset:3200
	s_movk_i32 s0, 0x1000
	v_add_co_u32_e64 v40, s[0:1], s0, v10
	s_nop 1
	v_addc_co_u32_e64 v41, s[0:1], 0, v11, s[0:1]
	global_load_dword v32, v[10:11], off offset:3456
	global_load_dword v33, v[10:11], off offset:3328
	global_load_dword v34, v[10:11], off offset:3712
	global_load_dword v35, v[10:11], off offset:3584
	global_load_dword v36, v[10:11], off offset:3968
	global_load_dword v37, v[10:11], off offset:3840
	global_load_dword v38, v[40:41], off
	global_load_dword v39, v[40:41], off offset:128
	s_mov_b32 s0, 0x358637bd
	v_ashrrev_i32_e32 v8, 6, v0
	v_and_b32_e32 v0, 63, v0
	v_cndmask_b32_e32 v0, v0, v8, vcc
	v_cvt_f32_i32_e32 v0, v0
	v_mul_f32_e32 v0, v14, v0
	v_mul_f32_e32 v8, 0.15915494, v0
	v_cos_f32_e32 v0, v8
	v_sin_f32_e32 v8, v8
	s_waitcnt vmcnt(0)
	v_lshlrev_b32_e32 v20, 16, v30
	v_and_b32_e32 v21, 0xffff0000, v30
	v_lshlrev_b32_e32 v22, 16, v31
	v_and_b32_e32 v23, 0xffff0000, v31
	v_pk_mul_f32 v[12:13], v[20:21], v[20:21]
	v_pk_mul_f32 v[24:25], v[22:23], v[22:23]
	v_mov_b32_e32 v27, v12
	v_mov_b32_e32 v26, v24
	v_mov_b32_e32 v12, v25
	v_pk_add_f32 v[12:13], v[26:27], v[12:13]
	s_nop 1
	v_add_f32_dpp v12, v12, v12 quad_perm:[1,0,3,2] row_mask:0xf bank_mask:0xf
	v_add_f32_dpp v13, v13, v13 quad_perm:[1,0,3,2] row_mask:0xf bank_mask:0xf
	s_nop 1
	v_add_f32_dpp v12, v12, v12 quad_perm:[2,3,0,1] row_mask:0xf bank_mask:0xf
	v_add_f32_dpp v13, v13, v13 quad_perm:[2,3,0,1] row_mask:0xf bank_mask:0xf
	s_nop 1
	v_add_f32_dpp v12, v12, v12 row_half_mirror row_mask:0xf bank_mask:0xf
	v_add_f32_dpp v13, v13, v13 row_half_mirror row_mask:0xf bank_mask:0xf
	s_nop 1
	v_add_f32_dpp v12, v12, v12 row_mirror row_mask:0xf bank_mask:0xf
	v_add_f32_dpp v13, v13, v13 row_mirror row_mask:0xf bank_mask:0xf
	v_mov_b32_e32 v24, v12
	v_mov_b32_e32 v25, v13
	s_nop 1
	v_permlane16_swap_b32 v12, v24
	v_permlane16_swap_b32 v13, v25
	s_nop 1
	v_add_f32_e32 v24, v12, v24
	v_add_f32_e32 v25, v13, v25
	v_mov_b64_e32 v[12:13], s[0:1]
	v_pk_fma_f32 v[24:25], v[24:25], s[8:9], v[12:13] op_sel_hi:[1,0,0]
	s_nop 0
	v_mul_f32_e32 v26, 0x4b800000, v25
	v_cmp_gt_f32_e64 s[38:39], s4, v25
	v_cmp_gt_f32_e64 s[0:1], s4, v24
	s_nop 0
	v_cndmask_b32_e64 v25, v25, v26, s[38:39]
	v_rsq_f32_e32 v25, v25
	s_nop 0
	v_mul_f32_e32 v26, 0x45800000, v25
	v_cndmask_b32_e64 v26, v25, v26, s[38:39]
	v_pk_mul_f32 v[20:21], v[26:27], v[20:21] op_sel_hi:[0,1]
	v_pk_mul_f32 v[20:21], v[2:3], v[20:21]
	s_nop 0
	v_pk_mul_f32 v[26:27], v[8:9], v[20:21] op_sel_hi:[0,1]
	v_pk_fma_f32 v[28:29], v[0:1], v[20:21], v[26:27] op_sel:[0,0,1] op_sel_hi:[1,1,0] neg_lo:[0,0,1] neg_hi:[0,0,1]
	v_pk_fma_f32 v[20:21], v[0:1], v[20:21], v[26:27] op_sel:[0,0,1] op_sel_hi:[0,1,0]
	v_mov_b32_e32 v29, v21
	v_pk_mul_f32 v[20:21], v[28:29], s[6:7] op_sel_hi:[1,0]
	s_nop 0
	v_cvt_pk_bf16_f32 v20, v20, v21
	global_store_dword v[10:11], v20, off offset:3072
	v_mul_f32_e32 v20, 0x4b800000, v24
	v_cndmask_b32_e64 v20, v24, v20, s[0:1]
	v_rsq_f32_e32 v20, v20
	s_nop 0
	v_mul_f32_e32 v21, 0x45800000, v20
	v_cndmask_b32_e64 v20, v20, v21, s[0:1]
	v_pk_mul_f32 v[20:21], v[20:21], v[22:23] op_sel_hi:[0,1]
	v_pk_mul_f32 v[20:21], v[2:3], v[20:21]
	s_nop 0
	v_pk_mul_f32 v[22:23], v[8:9], v[20:21] op_sel_hi:[0,1]
	v_pk_fma_f32 v[24:25], v[0:1], v[20:21], v[22:23] op_sel:[0,0,1] op_sel_hi:[1,1,0] neg_lo:[0,0,1] neg_hi:[0,0,1]
	v_pk_fma_f32 v[20:21], v[0:1], v[20:21], v[22:23] op_sel:[0,0,1] op_sel_hi:[0,1,0]
	v_mov_b32_e32 v25, v21
	v_pk_mul_f32 v[20:21], v[24:25], s[6:7] op_sel_hi:[1,0]
	v_cvt_pk_bf16_f32 v20, v20, v21
	v_lshlrev_b32_e32 v24, 16, v32
	global_store_dword v[10:11], v20, off offset:3200
	v_lshlrev_b32_e32 v20, 16, v33
	v_and_b32_e32 v21, 0xffff0000, v33
	v_and_b32_e32 v25, 0xffff0000, v32
	v_pk_mul_f32 v[22:23], v[20:21], v[20:21]
	v_pk_mul_f32 v[26:27], v[24:25], v[24:25]
	v_mov_b32_e32 v29, v22
	v_mov_b32_e32 v28, v26
	v_mov_b32_e32 v22, v27
	v_pk_add_f32 v[22:23], v[28:29], v[22:23]
	s_nop 1
	v_add_f32_dpp v22, v22, v22 quad_perm:[1,0,3,2] row_mask:0xf bank_mask:0xf
	v_add_f32_dpp v23, v23, v23 quad_perm:[1,0,3,2] row_mask:0xf bank_mask:0xf
	s_nop 1
	v_add_f32_dpp v22, v22, v22 quad_perm:[2,3,0,1] row_mask:0xf bank_mask:0xf
	v_add_f32_dpp v23, v23, v23 quad_perm:[2,3,0,1] row_mask:0xf bank_mask:0xf
	s_nop 1
	v_add_f32_dpp v22, v22, v22 row_half_mirror row_mask:0xf bank_mask:0xf
	v_add_f32_dpp v23, v23, v23 row_half_mirror row_mask:0xf bank_mask:0xf
	s_nop 1
	v_add_f32_dpp v22, v22, v22 row_mirror row_mask:0xf bank_mask:0xf
	v_add_f32_dpp v23, v23, v23 row_mirror row_mask:0xf bank_mask:0xf
	v_mov_b32_e32 v26, v22
	v_mov_b32_e32 v27, v23
	s_nop 1
	v_permlane16_swap_b32 v22, v26
	v_permlane16_swap_b32 v23, v27
	s_nop 1
	v_add_f32_e32 v22, v22, v26
	v_add_f32_e32 v23, v23, v27
	s_nop 0
	v_pk_fma_f32 v[22:23], v[22:23], s[8:9], v[12:13] op_sel_hi:[1,0,0]
	s_nop 0
	v_mul_f32_e32 v26, 0x4b800000, v23
	v_cmp_gt_f32_e64 s[38:39], s4, v23
	v_cmp_gt_f32_e64 s[0:1], s4, v22
	s_nop 0
	v_cndmask_b32_e64 v23, v23, v26, s[38:39]
	v_rsq_f32_e32 v23, v23
	s_nop 0
	v_mul_f32_e32 v26, 0x45800000, v23
	v_cndmask_b32_e64 v26, v23, v26, s[38:39]
	v_pk_mul_f32 v[20:21], v[26:27], v[20:21] op_sel_hi:[0,1]
	v_pk_mul_f32 v[20:21], v[2:3], v[20:21]
	s_nop 0
	v_pk_mul_f32 v[26:27], v[8:9], v[20:21] op_sel_hi:[0,1]
	v_pk_fma_f32 v[28:29], v[0:1], v[20:21], v[26:27] op_sel:[0,0,1] op_sel_hi:[1,1,0] neg_lo:[0,0,1] neg_hi:[0,0,1]
; DI float bflo(unsigned u) { return __uint_as_float(u << 16); }
; DI float bfhi(unsigned u) { return __uint_as_float(u & 0xffff0000u); }
; DI unsigned pack2(float lo, float hi) { f32x2_t v = {lo, hi}; return __builtin_bit_cast(unsigned, __builtin_convertvector(v, bf16x2_t)); }
; DI void bprep_phase(const Params& p) {
;     ...
;     for (int hd = 0; hd < 10; ++hd) {
;       const int col = (hd < 8) ? (1536 + hd * 64) : (2048 + (hd - 8) * 64);
;       unsigned u = rowp[(col >> 1) + pi];
;       float x1 = bflo(u), x2 = bfhi(u);
;       float ss = x1 * x1 + x2 * x2;
; #pragma unroll
;       for (int o = 16; o > 0; o >>= 1) ss += __shfl_xor(ss, o);
;       const float r = rsqrtf(ss * (1.0f / 64.0f) + EPS);
;       x1 = x1 * r * ((hd < 8) ? qg0 : kg0); x2 = x2 * r * ((hd < 8) ? qg1 : kg1);
;       const float qs = (hd < 8) ? 0.125f * LOG2E : 1.f;
;       rowp[(col >> 1) + pi] = pack2((x1 * cs - x2 * sn) * qs, (x1 * sn + x2 * cs) * qs);
;     }
	v_pk_fma_f32 v[20:21], v[0:1], v[20:21], v[26:27] op_sel:[0,0,1] op_sel_hi:[0,1,0]
	v_mov_b32_e32 v29, v21
	v_pk_mul_f32 v[20:21], v[28:29], s[6:7] op_sel_hi:[1,0]
	s_nop 0
	v_cvt_pk_bf16_f32 v20, v20, v21
	global_store_dword v[10:11], v20, off offset:3328
	v_mul_f32_e32 v20, 0x4b800000, v22
	v_cndmask_b32_e64 v20, v22, v20, s[0:1]
	v_rsq_f32_e32 v20, v20
	s_nop 0
	v_mul_f32_e32 v21, 0x45800000, v20
	v_cndmask_b32_e64 v20, v20, v21, s[0:1]
	v_pk_mul_f32 v[20:21], v[20:21], v[24:25] op_sel_hi:[0,1]
	v_pk_mul_f32 v[20:21], v[2:3], v[20:21]
	s_nop 0
	v_pk_mul_f32 v[22:23], v[8:9], v[20:21] op_sel_hi:[0,1]
	v_pk_fma_f32 v[24:25], v[0:1], v[20:21], v[22:23] op_sel:[0,0,1] op_sel_hi:[1,1,0] neg_lo:[0,0,1] neg_hi:[0,0,1]
	v_pk_fma_f32 v[20:21], v[0:1], v[20:21], v[22:23] op_sel:[0,0,1] op_sel_hi:[0,1,0]
	v_mov_b32_e32 v25, v21
	v_pk_mul_f32 v[20:21], v[24:25], s[6:7] op_sel_hi:[1,0]
	v_cvt_pk_bf16_f32 v20, v20, v21
	v_lshlrev_b32_e32 v24, 16, v34
	global_store_dword v[10:11], v20, off offset:3456
	v_lshlrev_b32_e32 v20, 16, v35
	v_and_b32_e32 v21, 0xffff0000, v35
	v_and_b32_e32 v25, 0xffff0000, v34
	v_pk_mul_f32 v[22:23], v[20:21], v[20:21]
	v_pk_mul_f32 v[26:27], v[24:25], v[24:25]
	v_mov_b32_e32 v29, v22
	v_mov_b32_e32 v28, v26
	v_mov_b32_e32 v22, v27
	v_pk_add_f32 v[22:23], v[28:29], v[22:23]
	s_nop 1
	v_add_f32_dpp v22, v22, v22 quad_perm:[1,0,3,2] row_mask:0xf bank_mask:0xf
	v_add_f32_dpp v23, v23, v23 quad_perm:[1,0,3,2] row_mask:0xf bank_mask:0xf
	s_nop 1
	v_add_f32_dpp v22, v22, v22 quad_perm:[2,3,0,1] row_mask:0xf bank_mask:0xf
	v_add_f32_dpp v23, v23, v23 quad_perm:[2,3,0,1] row_mask:0xf bank_mask:0xf
	s_nop 1
	v_add_f32_dpp v22, v22, v22 row_half_mirror row_mask:0xf bank_mask:0xf
	v_add_f32_dpp v23, v23, v23 row_half_mirror row_mask:0xf bank_mask:0xf
	s_nop 1
	v_add_f32_dpp v22, v22, v22 row_mirror row_mask:0xf bank_mask:0xf
	v_add_f32_dpp v23, v23, v23 row_mirror row_mask:0xf bank_mask:0xf
	v_mov_b32_e32 v26, v22
	v_mov_b32_e32 v27, v23
	s_nop 1
	v_permlane16_swap_b32 v22, v26
	v_permlane16_swap_b32 v23, v27
	s_nop 1
	v_add_f32_e32 v22, v22, v26
	v_add_f32_e32 v23, v23, v27
	s_nop 0
	v_pk_fma_f32 v[22:23], v[22:23], s[8:9], v[12:13] op_sel_hi:[1,0,0]
	s_nop 0
	v_mul_f32_e32 v26, 0x4b800000, v23
	v_cmp_gt_f32_e64 s[38:39], s4, v23
	v_cmp_gt_f32_e64 s[0:1], s4, v22
	s_nop 0
	v_cndmask_b32_e64 v23, v23, v26, s[38:39]
	v_rsq_f32_e32 v23, v23
	s_nop 0
	v_mul_f32_e32 v26, 0x45800000, v23
	v_cndmask_b32_e64 v26, v23, v26, s[38:39]
	v_pk_mul_f32 v[20:21], v[26:27], v[20:21] op_sel_hi:[0,1]
	v_pk_mul_f32 v[20:21], v[2:3], v[20:21]
	s_nop 0
	v_pk_mul_f32 v[26:27], v[8:9], v[20:21] op_sel_hi:[0,1]
	v_pk_fma_f32 v[28:29], v[0:1], v[20:21], v[26:27] op_sel:[0,0,1] op_sel_hi:[1,1,0] neg_lo:[0,0,1] neg_hi:[0,0,1]
	v_pk_fma_f32 v[20:21], v[0:1], v[20:21], v[26:27] op_sel:[0,0,1] op_sel_hi:[0,1,0]
	v_mov_b32_e32 v29, v21
	v_pk_mul_f32 v[20:21], v[28:29], s[6:7] op_sel_hi:[1,0]
	s_nop 0
	v_cvt_pk_bf16_f32 v20, v20, v21
	global_store_dword v[10:11], v20, off offset:3584
	v_mul_f32_e32 v20, 0x4b800000, v22
	v_cndmask_b32_e64 v20, v22, v20, s[0:1]
	v_rsq_f32_e32 v20, v20
	s_nop 0
	v_mul_f32_e32 v21, 0x45800000, v20
	v_cndmask_b32_e64 v20, v20, v21, s[0:1]
	v_pk_mul_f32 v[20:21], v[20:21], v[24:25] op_sel_hi:[0,1]
	v_pk_mul_f32 v[20:21], v[2:3], v[20:21]
	s_nop 0
	v_pk_mul_f32 v[22:23], v[8:9], v[20:21] op_sel_hi:[0,1]
	v_pk_fma_f32 v[24:25], v[0:1], v[20:21], v[22:23] op_sel:[0,0,1] op_sel_hi:[1,1,0] neg_lo:[0,0,1] neg_hi:[0,0,1]
	v_pk_fma_f32 v[20:21], v[0:1], v[20:21], v[22:23] op_sel:[0,0,1] op_sel_hi:[0,1,0]
	v_mov_b32_e32 v25, v21
	v_pk_mul_f32 v[20:21], v[24:25], s[6:7] op_sel_hi:[1,0]
	v_cvt_pk_bf16_f32 v20, v20, v21
	v_lshlrev_b32_e32 v24, 16, v36
	global_store_dword v[10:11], v20, off offset:3712
	v_lshlrev_b32_e32 v20, 16, v37
	v_and_b32_e32 v21, 0xffff0000, v37
	v_and_b32_e32 v25, 0xffff0000, v36
	v_pk_mul_f32 v[22:23], v[20:21], v[20:21]
	v_pk_mul_f32 v[26:27], v[24:25], v[24:25]
	v_mov_b32_e32 v29, v22
	v_mov_b32_e32 v28, v26
	v_mov_b32_e32 v22, v27
	v_pk_add_f32 v[22:23], v[28:29], v[22:23]
	s_nop 1
	v_add_f32_dpp v22, v22, v22 quad_perm:[1,0,3,2] row_mask:0xf bank_mask:0xf
	v_add_f32_dpp v23, v23, v23 quad_perm:[1,0,3,2] row_mask:0xf bank_mask:0xf
	s_nop 1
	v_add_f32_dpp v22, v22, v22 quad_perm:[2,3,0,1] row_mask:0xf bank_mask:0xf
	v_add_f32_dpp v23, v23, v23 quad_perm:[2,3,0,1] row_mask:0xf bank_mask:0xf
	s_nop 1
	v_add_f32_dpp v22, v22, v22 row_half_mirror row_mask:0xf bank_mask:0xf
	v_add_f32_dpp v23, v23, v23 row_half_mirror row_mask:0xf bank_mask:0xf
	s_nop 1
	v_add_f32_dpp v22, v22, v22 row_mirror row_mask:0xf bank_mask:0xf
	v_add_f32_dpp v23, v23, v23 row_mirror row_mask:0xf bank_mask:0xf
; DI float bflo(unsigned u) { return __uint_as_float(u << 16); }
; DI float bfhi(unsigned u) { return __uint_as_float(u & 0xffff0000u); }
; DI unsigned pack2(float lo, float hi) { f32x2_t v = {lo, hi}; return __builtin_bit_cast(unsigned, __builtin_convertvector(v, bf16x2_t)); }
; DI void bprep_phase(const Params& p) {
;     ...
;     for (int hd = 0; hd < 10; ++hd) {
;       const int col = (hd < 8) ? (1536 + hd * 64) : (2048 + (hd - 8) * 64);
;       unsigned u = rowp[(col >> 1) + pi];
;       float x1 = bflo(u), x2 = bfhi(u);
;       float ss = x1 * x1 + x2 * x2;
; #pragma unroll
;       for (int o = 16; o > 0; o >>= 1) ss += __shfl_xor(ss, o);
;       const float r = rsqrtf(ss * (1.0f / 64.0f) + EPS);
;       x1 = x1 * r * ((hd < 8) ? qg0 : kg0); x2 = x2 * r * ((hd < 8) ? qg1 : kg1);
;       const float qs = (hd < 8) ? 0.125f * LOG2E : 1.f;
;       rowp[(col >> 1) + pi] = pack2((x1 * cs - x2 * sn) * qs, (x1 * sn + x2 * cs) * qs);
;     }
;   }
	v_mov_b32_e32 v26, v22
	v_mov_b32_e32 v27, v23
	s_nop 1
	v_permlane16_swap_b32 v22, v26
	v_permlane16_swap_b32 v23, v27
	s_nop 1
	v_add_f32_e32 v22, v22, v26
	v_add_f32_e32 v23, v23, v27
	s_nop 0
	v_pk_fma_f32 v[22:23], v[22:23], s[8:9], v[12:13] op_sel_hi:[1,0,0]
	s_nop 0
	v_mul_f32_e32 v26, 0x4b800000, v23
	v_cmp_gt_f32_e64 s[38:39], s4, v23
	v_cmp_gt_f32_e64 s[0:1], s4, v22
	s_nop 0
	v_cndmask_b32_e64 v23, v23, v26, s[38:39]
	v_rsq_f32_e32 v23, v23
	s_nop 0
	v_mul_f32_e32 v26, 0x45800000, v23
	v_cndmask_b32_e64 v26, v23, v26, s[38:39]
	v_pk_mul_f32 v[20:21], v[26:27], v[20:21] op_sel_hi:[0,1]
	v_pk_mul_f32 v[20:21], v[2:3], v[20:21]
	s_nop 0
	v_pk_mul_f32 v[26:27], v[8:9], v[20:21] op_sel_hi:[0,1]
	v_pk_fma_f32 v[28:29], v[0:1], v[20:21], v[26:27] op_sel:[0,0,1] op_sel_hi:[1,1,0] neg_lo:[0,0,1] neg_hi:[0,0,1]
	v_pk_fma_f32 v[20:21], v[0:1], v[20:21], v[26:27] op_sel:[0,0,1] op_sel_hi:[0,1,0]
	v_mov_b32_e32 v29, v21
	v_pk_mul_f32 v[20:21], v[28:29], s[6:7] op_sel_hi:[1,0]
	s_nop 0
	v_cvt_pk_bf16_f32 v20, v20, v21
	global_store_dword v[10:11], v20, off offset:3840
	v_mul_f32_e32 v20, 0x4b800000, v22
	v_cndmask_b32_e64 v20, v22, v20, s[0:1]
	v_rsq_f32_e32 v20, v20
	s_nop 0
	v_mul_f32_e32 v21, 0x45800000, v20
	v_cndmask_b32_e64 v20, v20, v21, s[0:1]
	v_pk_mul_f32 v[20:21], v[20:21], v[24:25] op_sel_hi:[0,1]
	v_pk_mul_f32 v[20:21], v[2:3], v[20:21]
	s_movk_i32 s0, 0x1000
	v_pk_mul_f32 v[22:23], v[8:9], v[20:21] op_sel_hi:[0,1]
	v_pk_fma_f32 v[24:25], v[0:1], v[20:21], v[22:23] op_sel:[0,0,1] op_sel_hi:[1,1,0] neg_lo:[0,0,1] neg_hi:[0,0,1]
	v_pk_fma_f32 v[20:21], v[0:1], v[20:21], v[22:23] op_sel:[0,0,1] op_sel_hi:[0,1,0]
	v_mov_b32_e32 v25, v21
	v_pk_mul_f32 v[20:21], v[24:25], s[6:7] op_sel_hi:[1,0]
	s_nop 0
	v_cvt_pk_bf16_f32 v20, v20, v21
	global_store_dword v[10:11], v20, off offset:3968
	v_add_co_u32_e64 v10, s[0:1], s0, v10
	s_nop 1
	v_addc_co_u32_e64 v11, s[0:1], 0, v11, s[0:1]
	v_lshlrev_b32_e32 v20, 16, v38
	v_and_b32_e32 v21, 0xffff0000, v38
	v_lshlrev_b32_e32 v24, 16, v39
	v_and_b32_e32 v25, 0xffff0000, v39
	v_pk_mul_f32 v[22:23], v[20:21], v[20:21]
	v_pk_mul_f32 v[26:27], v[24:25], v[24:25]
	v_mov_b32_e32 v29, v22
	v_mov_b32_e32 v28, v26
	v_mov_b32_e32 v22, v27
	v_pk_add_f32 v[22:23], v[28:29], v[22:23]
	s_nop 1
	v_add_f32_dpp v22, v22, v22 quad_perm:[1,0,3,2] row_mask:0xf bank_mask:0xf
	v_add_f32_dpp v23, v23, v23 quad_perm:[1,0,3,2] row_mask:0xf bank_mask:0xf
	s_nop 1
	v_add_f32_dpp v22, v22, v22 quad_perm:[2,3,0,1] row_mask:0xf bank_mask:0xf
	v_add_f32_dpp v23, v23, v23 quad_perm:[2,3,0,1] row_mask:0xf bank_mask:0xf
	s_nop 1
	v_add_f32_dpp v22, v22, v22 row_half_mirror row_mask:0xf bank_mask:0xf
	v_add_f32_dpp v23, v23, v23 row_half_mirror row_mask:0xf bank_mask:0xf
	s_nop 1
	v_add_f32_dpp v22, v22, v22 row_mirror row_mask:0xf bank_mask:0xf
	v_add_f32_dpp v23, v23, v23 row_mirror row_mask:0xf bank_mask:0xf
	v_mov_b32_e32 v26, v22
	v_mov_b32_e32 v27, v23
	s_nop 1
	v_permlane16_swap_b32 v22, v26
	v_permlane16_swap_b32 v23, v27
	s_nop 1
	v_add_f32_e32 v22, v22, v26
	v_add_f32_e32 v23, v23, v27
	s_nop 0
	v_pk_fma_f32 v[12:13], v[22:23], s[8:9], v[12:13] op_sel_hi:[1,0,0]
	s_nop 0
	v_mul_f32_e32 v22, 0x4b800000, v13
	v_cmp_gt_f32_e64 s[38:39], s4, v13
	v_cmp_gt_f32_e64 s[0:1], s4, v12
	s_nop 0
	v_cndmask_b32_e64 v13, v13, v22, s[38:39]
	v_rsq_f32_e32 v13, v13
	s_nop 0
	v_mul_f32_e32 v22, 0x45800000, v13
	v_cndmask_b32_e64 v22, v13, v22, s[38:39]
	v_pk_mul_f32 v[20:21], v[22:23], v[20:21] op_sel_hi:[0,1]
	v_pk_mul_f32 v[20:21], v[4:5], v[20:21]
	s_nop 0
	v_pk_mul_f32 v[22:23], v[8:9], v[20:21] op_sel_hi:[0,1]
	v_pk_fma_f32 v[26:27], v[0:1], v[20:21], v[22:23] op_sel:[0,0,1] op_sel_hi:[1,1,0] neg_lo:[0,0,1] neg_hi:[0,0,1]
	v_pk_fma_f32 v[20:21], v[0:1], v[20:21], v[22:23] op_sel:[0,0,1] op_sel_hi:[0,1,0]
	v_cvt_pk_bf16_f32 v13, v26, v21
	global_store_dword v[10:11], v13, off
	v_mul_f32_e32 v13, 0x4b800000, v12
	v_cndmask_b32_e64 v12, v12, v13, s[0:1]
	v_rsq_f32_e32 v12, v12
	s_nop 0
	v_mul_f32_e32 v13, 0x45800000, v12
	v_cndmask_b32_e64 v12, v12, v13, s[0:1]
	v_pk_mul_f32 v[12:13], v[12:13], v[24:25] op_sel_hi:[0,1]
	v_pk_mul_f32 v[12:13], v[4:5], v[12:13]
	s_nop 0
	v_pk_mul_f32 v[20:21], v[8:9], v[12:13] op_sel_hi:[0,1]
	v_add_u32_e32 v9, s17, v9
	v_pk_fma_f32 v[22:23], v[0:1], v[12:13], v[20:21] op_sel:[0,0,1] op_sel_hi:[1,1,0] neg_lo:[0,0,1] neg_hi:[0,0,1]
	v_pk_fma_f32 v[12:13], v[0:1], v[12:13], v[20:21] op_sel:[0,0,1] op_sel_hi:[0,1,0]
	v_cmp_lt_i32_e64 s[0:1], s63, v9
	v_cvt_pk_bf16_f32 v0, v22, v13
	s_or_b64 s[40:41], s[0:1], s[40:41]
	global_store_dword v[10:11], v0, off offset:128
	s_andn2_b64 exec, exec, s[40:41]
	s_cbranch_execnz .LBB0_249

; DI bf16_t f2bf(float x) { unsigned u = __float_as_uint(x); u += 0x7fffu + ((u >> 16) & 1u); return (bf16_t)(u >> 16); }
; DI unsigned pack2(float lo, float hi) { f32x2_t v = {lo, hi}; return __builtin_bit_cast(unsigned, __builtin_convertvector(v, bf16x2_t)); }
; #define PG8_LAS __attribute__((address_space(3)))
;   DI void operator()(const f32x4 (&acc)[2][2][4][2], const Unit& u, int wr, int wc, int fr, int fq, const PG8_LAS float*) const {
;     const int row0 = u.pm * BM + wr * 64 + fr, col0 = u.pn * BM + wc * 32 + 8 * fq;
; #pragma unroll
;     for (int ai = 0; ai < 2; ++ai)
; #pragma unroll
;       for (int m = 0; m < 4; ++m) { const int row = row0 + ai * HALF + m * 16; bf16_t* rowp = dst + (size_t)row * DM + col0; float ss = 0.f;
; #pragma unroll
;         for (int bj = 0; bj < 2; ++bj) { const f32x4 v0 = acc[ai][bj][m][0] * coef, v1 = acc[ai][bj][m][1] * coef;
;           ss += v0[0] * v0[0] + v0[1] * v0[1] + v0[2] * v0[2] + v0[3] * v0[3] + v1[0] * v1[0] + v1[1] * v1[1] + v1[2] * v1[2] + v1[3] * v1[3];
;           u32x4 w; w.x = pack2(v0[0], v0[1]); w.y = pack2(v0[2], v0[3]); w.z = pack2(v1[0], v1[1]); w.w = pack2(v1[2], v1[3]);
;           *(u32x4*)(rowp + bj * HALF) = w; }
;         ss += __shfl_xor(ss, 16); ss += __shfl_xor(ss, 32);
;         if (fq == 0) ssq[(size_t)row * 16 + u.pn * 4 + wc] = f2bf(ss); }
.Leinit511_skip:
	v_mul_f32_e32 v152, v119, v119
	v_fmac_f32_e32 v152, v118, v118
	v_fmac_f32_e32 v152, v120, v120
	v_cvt_pk_bf16_f32 v118, v118, v119
	v_cvt_pk_bf16_f32 v119, v120, v121
	v_mul_f32_e32 v120, v123, v123
	v_fmac_f32_e32 v120, v122, v122
	v_fmac_f32_e32 v120, v124, v124
	v_fmac_f32_e32 v152, v121, v121
	v_fmac_f32_e32 v120, v125, v125
	v_fmac_f32_e32 v152, v110, v110
	v_fmac_f32_e32 v120, v126, v126
	v_xor_b32_e32 v143, 16, v223
	v_fmac_f32_e32 v152, v111, v111
	v_fmac_f32_e32 v120, v127, v127
	v_cmp_lt_i32_e64 s[0:1], v143, v225
	v_fmac_f32_e32 v152, v112, v112
	v_fmac_f32_e32 v120, v128, v128
	v_cndmask_b32_e64 v143, v223, v143, s[0:1]
	v_fmac_f32_e32 v152, v113, v113
	v_fmac_f32_e32 v120, v129, v129
	v_lshlrev_b32_e32 v149, 2, v143
	v_add_f32_e32 v152, v152, v120
	v_mov_b32_e32 v153, v152
	s_nop 1
	v_permlane16_swap_b32 v152, v153
	v_xor_b32_e32 v143, 32, v223
	v_cmp_lt_i32_e64 s[0:1], v143, v225
	v_lshl_add_u32 v142, s21, 8, v144
	v_cvt_pk_bf16_f32 v120, v110, v111
	v_cndmask_b32_e64 v143, v223, v143, s[0:1]
	v_lshlrev_b32_e32 v148, 2, v143
	s_waitcnt lgkmcnt(0)
	v_add_f32_e32 v110, v152, v153
	v_ashrrev_i32_e32 v143, 31, v142
	v_mov_b32_e32 v111, v110
	s_nop 1
	v_permlane32_swap_b32 v110, v111
	v_lshl_or_b32 v140, s20, 8, v147
	v_lshlrev_b64 v[150:151], 11, v[142:143]
	v_ashrrev_i32_e32 v141, 31, v140
	v_lshl_add_u64 v[150:151], s[92:93], 0, v[150:151]
	s_lshl_b32 s0, s20, 2
	v_lshl_add_u64 v[150:151], v[140:141], 1, v[150:151]
	v_cvt_pk_bf16_f32 v121, v112, v113
	s_ashr_i32 s1, s0, 31
	global_store_dwordx4 v[150:151], v[118:121], off
	s_nop 1
	v_cvt_pk_bf16_f32 v118, v122, v123
	v_cvt_pk_bf16_f32 v119, v124, v125
	v_cvt_pk_bf16_f32 v120, v126, v127
	v_cvt_pk_bf16_f32 v121, v128, v129
	global_store_dwordx4 v[150:151], v[118:121], off offset:256
	s_and_saveexec_b64 s[28:29], s[36:37]
	s_cbranch_execz .LBB0_514
	s_waitcnt lgkmcnt(0)
	v_add_f32_e32 v110, v110, v111
	v_bfe_u32 v111, v110, 16, 1
	v_add3_u32 v112, v110, v111, s63
	v_lshlrev_b64 v[110:111], 5, v[142:143]
	v_lshl_add_u64 v[110:111], s[70:71], 0, v[110:111]
	v_lshl_add_u64 v[110:111], s[0:1], 1, v[110:111]
	s_lshl_b32 s76, s5, 1
	v_lshl_add_u64 v[110:111], v[110:111], 0, s[76:77]
	global_store_short_d16_hi v[110:111], v112, off
.LBB0_514:
	s_or_b64 exec, exec, s[28:29]
	v_mul_f32_e32 v118, v91, v91
	v_fmac_f32_e32 v118, v90, v90
	v_fmac_f32_e32 v118, v92, v92
	v_cvt_pk_bf16_f32 v90, v90, v91
	v_cvt_pk_bf16_f32 v91, v92, v93
	v_mul_f32_e32 v92, v103, v103
	v_fmac_f32_e32 v92, v102, v102
	v_fmac_f32_e32 v92, v104, v104
	v_fmac_f32_e32 v118, v93, v93
	v_fmac_f32_e32 v92, v105, v105
	v_fmac_f32_e32 v118, v82, v82
	v_fmac_f32_e32 v92, v114, v114
	v_fmac_f32_e32 v118, v83, v83
	v_fmac_f32_e32 v92, v115, v115
	v_fmac_f32_e32 v118, v84, v84
	v_fmac_f32_e32 v92, v116, v116
	v_fmac_f32_e32 v118, v85, v85
	v_fmac_f32_e32 v92, v117, v117
	v_add_f32_e32 v118, v118, v92
	v_mov_b32_e32 v119, v118
	s_nop 1
	v_permlane16_swap_b32 v118, v119
	v_or_b32_e32 v110, 16, v142
	v_cvt_pk_bf16_f32 v92, v82, v83
	s_waitcnt lgkmcnt(0)
	v_ashrrev_i32_e32 v111, 31, v110
	v_lshlrev_b64 v[112:113], 11, v[110:111]
	v_add_f32_e32 v82, v118, v119
	v_mov_b32_e32 v83, v82
	s_nop 1
	v_permlane32_swap_b32 v82, v83
	v_lshl_add_u64 v[112:113], s[92:93], 0, v[112:113]
	v_lshl_add_u64 v[112:113], v[140:141], 1, v[112:113]
	v_cvt_pk_bf16_f32 v93, v84, v85
	global_store_dwordx4 v[112:113], v[90:93], off
	s_nop 1
	v_cvt_pk_bf16_f32 v90, v102, v103
	v_cvt_pk_bf16_f32 v91, v104, v105
	v_cvt_pk_bf16_f32 v92, v114, v115
	v_cvt_pk_bf16_f32 v93, v116, v117
	global_store_dwordx4 v[112:113], v[90:93], off offset:256
	s_and_saveexec_b64 s[28:29], s[36:37]
	s_cbranch_execz .LBB0_516
	s_waitcnt lgkmcnt(0)
	v_add_f32_e32 v82, v82, v83
	v_bfe_u32 v83, v82, 16, 1
	v_add3_u32 v84, v82, v83, s63
	v_lshlrev_b64 v[82:83], 5, v[110:111]
	v_lshl_add_u64 v[82:83], s[70:71], 0, v[82:83]
	v_lshl_add_u64 v[82:83], s[0:1], 1, v[82:83]
	s_lshl_b32 s76, s5, 1
	v_lshl_add_u64 v[82:83], v[82:83], 0, s[76:77]
	global_store_short_d16_hi v[82:83], v84, off
.LBB0_516:
	s_or_b64 exec, exec, s[28:29]
	v_mul_f32_e32 v90, v63, v63
	v_fmac_f32_e32 v90, v62, v62
	v_fmac_f32_e32 v90, v64, v64
	v_cvt_pk_bf16_f32 v62, v62, v63
	v_cvt_pk_bf16_f32 v63, v64, v65
	v_mul_f32_e32 v64, v87, v87
	v_fmac_f32_e32 v64, v86, v86
	v_fmac_f32_e32 v64, v88, v88
	v_fmac_f32_e32 v90, v65, v65
	v_fmac_f32_e32 v64, v89, v89
	v_fmac_f32_e32 v90, v50, v50
	v_fmac_f32_e32 v64, v98, v98
	v_fmac_f32_e32 v90, v51, v51
	v_fmac_f32_e32 v64, v99, v99
	v_fmac_f32_e32 v90, v52, v52
	v_fmac_f32_e32 v64, v100, v100
	v_fmac_f32_e32 v90, v53, v53
	v_fmac_f32_e32 v64, v101, v101
	v_add_f32_e32 v90, v90, v64
	v_mov_b32_e32 v91, v90
	s_nop 1
	v_permlane16_swap_b32 v90, v91
	v_or_b32_e32 v82, 32, v142
	v_cvt_pk_bf16_f32 v64, v50, v51
	s_waitcnt lgkmcnt(0)
	v_ashrrev_i32_e32 v83, 31, v82
	v_lshlrev_b64 v[84:85], 11, v[82:83]
	v_add_f32_e32 v50, v90, v91
	v_mov_b32_e32 v51, v50
	s_nop 1
	v_permlane32_swap_b32 v50, v51
	v_lshl_add_u64 v[84:85], s[92:93], 0, v[84:85]
	v_lshl_add_u64 v[84:85], v[140:141], 1, v[84:85]
	v_cvt_pk_bf16_f32 v65, v52, v53
	global_store_dwordx4 v[84:85], v[62:65], off
	s_nop 1
	v_cvt_pk_bf16_f32 v62, v86, v87
	v_cvt_pk_bf16_f32 v63, v88, v89
	v_cvt_pk_bf16_f32 v64, v98, v99
	v_cvt_pk_bf16_f32 v65, v100, v101
	global_store_dwordx4 v[84:85], v[62:65], off offset:256
	s_and_saveexec_b64 s[28:29], s[36:37]
	s_cbranch_execz .LBB0_518
	s_waitcnt lgkmcnt(0)
	v_add_f32_e32 v50, v50, v51
	v_bfe_u32 v51, v50, 16, 1
	v_add3_u32 v52, v50, v51, s63
	v_lshlrev_b64 v[50:51], 5, v[82:83]
	v_lshl_add_u64 v[50:51], s[70:71], 0, v[50:51]
	v_lshl_add_u64 v[50:51], s[0:1], 1, v[50:51]
	s_lshl_b32 s76, s5, 1
	v_lshl_add_u64 v[50:51], v[50:51], 0, s[76:77]
	global_store_short_d16_hi v[50:51], v52, off
; DI bf16_t f2bf(float x) { unsigned u = __float_as_uint(x); u += 0x7fffu + ((u >> 16) & 1u); return (bf16_t)(u >> 16); }
; DI unsigned pack2(float lo, float hi) { f32x2_t v = {lo, hi}; return __builtin_bit_cast(unsigned, __builtin_convertvector(v, bf16x2_t)); }
;   DI void operator()(const f32x4 (&acc)[2][2][4][2], const Unit& u, int wr, int wc, int fr, int fq, const PG8_LAS float*) const {
;     ...
;       for (int m = 0; m < 4; ++m) { const int row = row0 + ai * HALF + m * 16; bf16_t* rowp = dst + (size_t)row * DM + col0; float ss = 0.f;
; #pragma unroll
;         for (int bj = 0; bj < 2; ++bj) { const f32x4 v0 = acc[ai][bj][m][0] * coef, v1 = acc[ai][bj][m][1] * coef;
;           ss += v0[0] * v0[0] + v0[1] * v0[1] + v0[2] * v0[2] + v0[3] * v0[3] + v1[0] * v1[0] + v1[1] * v1[1] + v1[2] * v1[2] + v1[3] * v1[3];
;           u32x4 w; w.x = pack2(v0[0], v0[1]); w.y = pack2(v0[2], v0[3]); w.z = pack2(v1[0], v1[1]); w.w = pack2(v1[2], v1[3]);
;           *(u32x4*)(rowp + bj * HALF) = w; }
;         ss += __shfl_xor(ss, 16); ss += __shfl_xor(ss, 32);
;         if (fq == 0) ssq[(size_t)row * 16 + u.pn * 4 + wc] = f2bf(ss); }
.LBB0_518:
	s_or_b64 exec, exec, s[28:29]
	v_mul_f32_e32 v62, v43, v43
	v_fmac_f32_e32 v62, v42, v42
	v_fmac_f32_e32 v62, v44, v44
	v_cvt_pk_bf16_f32 v42, v42, v43
	v_cvt_pk_bf16_f32 v43, v44, v45
	v_mul_f32_e32 v44, v59, v59
	v_fmac_f32_e32 v44, v58, v58
	v_fmac_f32_e32 v44, v60, v60
	v_fmac_f32_e32 v62, v45, v45
	v_fmac_f32_e32 v44, v61, v61
	v_fmac_f32_e32 v62, v22, v22
	v_fmac_f32_e32 v44, v74, v74
	v_fmac_f32_e32 v62, v23, v23
	v_fmac_f32_e32 v44, v75, v75
	v_fmac_f32_e32 v62, v24, v24
	v_fmac_f32_e32 v44, v76, v76
	v_fmac_f32_e32 v62, v25, v25
	v_fmac_f32_e32 v44, v77, v77
	v_add_f32_e32 v62, v62, v44
	v_mov_b32_e32 v63, v62
	s_nop 1
	v_permlane16_swap_b32 v62, v63
	v_or_b32_e32 v50, 48, v142
	v_cvt_pk_bf16_f32 v44, v22, v23
	s_waitcnt lgkmcnt(0)
	v_ashrrev_i32_e32 v51, 31, v50
	v_lshlrev_b64 v[52:53], 11, v[50:51]
	v_add_f32_e32 v22, v62, v63
	v_mov_b32_e32 v23, v22
	s_nop 1
	v_permlane32_swap_b32 v22, v23
	v_lshl_add_u64 v[52:53], s[92:93], 0, v[52:53]
	v_lshl_add_u64 v[52:53], v[140:141], 1, v[52:53]
	v_cvt_pk_bf16_f32 v45, v24, v25
	global_store_dwordx4 v[52:53], v[42:45], off
	s_nop 1
	v_cvt_pk_bf16_f32 v42, v58, v59
	v_cvt_pk_bf16_f32 v43, v60, v61
	v_cvt_pk_bf16_f32 v44, v74, v75
	v_cvt_pk_bf16_f32 v45, v76, v77
	global_store_dwordx4 v[52:53], v[42:45], off offset:256
	s_and_saveexec_b64 s[28:29], s[36:37]
	s_cbranch_execz .LBB0_520
	s_waitcnt lgkmcnt(0)
	v_add_f32_e32 v22, v22, v23
	v_bfe_u32 v23, v22, 16, 1
	v_add3_u32 v24, v22, v23, s63
	v_lshlrev_b64 v[22:23], 5, v[50:51]
	v_lshl_add_u64 v[22:23], s[70:71], 0, v[22:23]
	v_lshl_add_u64 v[22:23], s[0:1], 1, v[22:23]
	s_lshl_b32 s76, s5, 1
	v_lshl_add_u64 v[22:23], v[22:23], 0, s[76:77]
	global_store_short_d16_hi v[22:23], v24, off
.LBB0_520:
	s_or_b64 exec, exec, s[28:29]
	v_mul_f32_e32 v42, v39, v39
	v_fmac_f32_e32 v42, v38, v38
	v_fmac_f32_e32 v42, v40, v40
	v_cvt_pk_bf16_f32 v38, v38, v39
	v_cvt_pk_bf16_f32 v39, v40, v41
	v_mul_f32_e32 v40, v55, v55
	v_fmac_f32_e32 v40, v54, v54
	v_fmac_f32_e32 v40, v56, v56
	v_fmac_f32_e32 v42, v41, v41
	v_fmac_f32_e32 v40, v57, v57
	v_fmac_f32_e32 v42, v18, v18
	v_fmac_f32_e32 v40, v66, v66
	v_fmac_f32_e32 v42, v19, v19
	v_fmac_f32_e32 v40, v67, v67
	v_fmac_f32_e32 v42, v20, v20
	v_fmac_f32_e32 v40, v68, v68
	v_fmac_f32_e32 v42, v21, v21
	v_fmac_f32_e32 v40, v69, v69
	v_add_f32_e32 v42, v42, v40
	v_mov_b32_e32 v43, v42
	s_nop 1
	v_permlane16_swap_b32 v42, v43
	v_add_u32_e32 v22, 0x80, v142
	v_cvt_pk_bf16_f32 v40, v18, v19
	s_waitcnt lgkmcnt(0)
	v_ashrrev_i32_e32 v23, 31, v22
	v_lshlrev_b64 v[24:25], 11, v[22:23]
	v_add_f32_e32 v18, v42, v43
	v_mov_b32_e32 v19, v18
	s_nop 1
	v_permlane32_swap_b32 v18, v19
	v_lshl_add_u64 v[24:25], s[92:93], 0, v[24:25]
	v_lshl_add_u64 v[24:25], v[140:141], 1, v[24:25]
	v_cvt_pk_bf16_f32 v41, v20, v21
	global_store_dwordx4 v[24:25], v[38:41], off
	s_nop 1
	v_cvt_pk_bf16_f32 v38, v54, v55
	v_cvt_pk_bf16_f32 v39, v56, v57
	v_cvt_pk_bf16_f32 v40, v66, v67
	v_cvt_pk_bf16_f32 v41, v68, v69
	global_store_dwordx4 v[24:25], v[38:41], off offset:256
	s_and_saveexec_b64 s[28:29], s[36:37]
	s_cbranch_execz .LBB0_522
	s_waitcnt lgkmcnt(0)
	v_add_f32_e32 v18, v18, v19
	v_bfe_u32 v19, v18, 16, 1
	v_add3_u32 v20, v18, v19, s63
	v_lshlrev_b64 v[18:19], 5, v[22:23]
	v_lshl_add_u64 v[18:19], s[70:71], 0, v[18:19]
	v_lshl_add_u64 v[18:19], s[0:1], 1, v[18:19]
	s_lshl_b32 s76, s5, 1
	v_lshl_add_u64 v[18:19], v[18:19], 0, s[76:77]
	global_store_short_d16_hi v[18:19], v20, off
; DI bf16_t f2bf(float x) { unsigned u = __float_as_uint(x); u += 0x7fffu + ((u >> 16) & 1u); return (bf16_t)(u >> 16); }
; DI unsigned pack2(float lo, float hi) { f32x2_t v = {lo, hi}; return __builtin_bit_cast(unsigned, __builtin_convertvector(v, bf16x2_t)); }
;   DI void operator()(const f32x4 (&acc)[2][2][4][2], const Unit& u, int wr, int wc, int fr, int fq, const PG8_LAS float*) const {
;     ...
;       for (int m = 0; m < 4; ++m) { const int row = row0 + ai * HALF + m * 16; bf16_t* rowp = dst + (size_t)row * DM + col0; float ss = 0.f;
; #pragma unroll
;         for (int bj = 0; bj < 2; ++bj) { const f32x4 v0 = acc[ai][bj][m][0] * coef, v1 = acc[ai][bj][m][1] * coef;
;           ss += v0[0] * v0[0] + v0[1] * v0[1] + v0[2] * v0[2] + v0[3] * v0[3] + v1[0] * v1[0] + v1[1] * v1[1] + v1[2] * v1[2] + v1[3] * v1[3];
;           u32x4 w; w.x = pack2(v0[0], v0[1]); w.y = pack2(v0[2], v0[3]); w.z = pack2(v1[0], v1[1]); w.w = pack2(v1[2], v1[3]);
;           *(u32x4*)(rowp + bj * HALF) = w; }
;         ss += __shfl_xor(ss, 16); ss += __shfl_xor(ss, 32);
;         if (fq == 0) ssq[(size_t)row * 16 + u.pn * 4 + wc] = f2bf(ss); }
.LBB0_522:
	s_or_b64 exec, exec, s[28:29]
	v_mul_f32_e32 v22, v11, v11
	v_fmac_f32_e32 v22, v10, v10
	v_fmac_f32_e32 v22, v12, v12
	v_cvt_pk_bf16_f32 v10, v10, v11
	v_cvt_pk_bf16_f32 v11, v12, v13
	v_mul_f32_e32 v12, v95, v95
	v_fmac_f32_e32 v12, v94, v94
	v_fmac_f32_e32 v12, v96, v96
	v_fmac_f32_e32 v22, v13, v13
	v_fmac_f32_e32 v12, v97, v97
	v_fmac_f32_e32 v22, v2, v2
	v_fmac_f32_e32 v12, v106, v106
	v_fmac_f32_e32 v22, v3, v3
	v_fmac_f32_e32 v12, v107, v107
	v_fmac_f32_e32 v22, v4, v4
	v_fmac_f32_e32 v12, v108, v108
	v_fmac_f32_e32 v22, v5, v5
	v_fmac_f32_e32 v12, v109, v109
	v_add_f32_e32 v22, v22, v12
	v_mov_b32_e32 v23, v22
	s_nop 1
	v_permlane16_swap_b32 v22, v23
	v_add_u32_e32 v18, 0x90, v142
	v_cvt_pk_bf16_f32 v12, v2, v3
	s_waitcnt lgkmcnt(0)
	v_ashrrev_i32_e32 v19, 31, v18
	v_lshlrev_b64 v[20:21], 11, v[18:19]
	v_add_f32_e32 v2, v22, v23
	v_mov_b32_e32 v3, v2
	s_nop 1
	v_permlane32_swap_b32 v2, v3
	v_lshl_add_u64 v[20:21], s[92:93], 0, v[20:21]
	v_lshl_add_u64 v[20:21], v[140:141], 1, v[20:21]
	v_cvt_pk_bf16_f32 v13, v4, v5
	global_store_dwordx4 v[20:21], v[10:13], off
	s_nop 1
	v_cvt_pk_bf16_f32 v10, v94, v95
	v_cvt_pk_bf16_f32 v11, v96, v97
	v_cvt_pk_bf16_f32 v12, v106, v107
	v_cvt_pk_bf16_f32 v13, v108, v109
	global_store_dwordx4 v[20:21], v[10:13], off offset:256
	s_and_saveexec_b64 s[28:29], s[36:37]
	s_cbranch_execz .LBB0_524
	s_waitcnt lgkmcnt(0)
	v_add_f32_e32 v2, v2, v3
	v_bfe_u32 v3, v2, 16, 1
	v_add3_u32 v4, v2, v3, s63
	v_lshlrev_b64 v[2:3], 5, v[18:19]
	v_lshl_add_u64 v[2:3], s[70:71], 0, v[2:3]
	v_lshl_add_u64 v[2:3], s[0:1], 1, v[2:3]
	s_lshl_b32 s76, s5, 1
	v_lshl_add_u64 v[2:3], v[2:3], 0, s[76:77]
	global_store_short_d16_hi v[2:3], v4, off
.LBB0_524:
	s_or_b64 exec, exec, s[28:29]
	v_add_u32_e32 v2, 0xa0, v142
	s_waitcnt lgkmcnt(0)
	v_ashrrev_i32_e32 v3, 31, v2
	v_lshlrev_b64 v[4:5], 11, v[2:3]
	v_lshl_add_u64 v[4:5], s[92:93], 0, v[4:5]
	v_lshl_add_u64 v[18:19], v[140:141], 1, v[4:5]
	v_mul_f32_e32 v4, v47, v47
	v_mul_f32_e32 v5, v71, v71
	v_fmac_f32_e32 v4, v46, v46
	v_fmac_f32_e32 v5, v70, v70
	v_fmac_f32_e32 v4, v48, v48
	v_fmac_f32_e32 v5, v72, v72
	v_fmac_f32_e32 v4, v49, v49
	v_fmac_f32_e32 v5, v73, v73
	v_fmac_f32_e32 v4, v30, v30
	v_fmac_f32_e32 v5, v78, v78
	v_fmac_f32_e32 v4, v31, v31
	v_fmac_f32_e32 v5, v79, v79
	v_fmac_f32_e32 v4, v32, v32
	v_fmac_f32_e32 v5, v80, v80
	v_fmac_f32_e32 v4, v33, v33
	v_fmac_f32_e32 v5, v81, v81
	v_add_f32_e32 v4, v4, v5
	v_mov_b32_e32 v5, v4
	s_nop 1
	v_permlane16_swap_b32 v4, v5
	v_cvt_pk_bf16_f32 v10, v46, v47
	v_cvt_pk_bf16_f32 v11, v48, v49
	v_cvt_pk_bf16_f32 v12, v30, v31
	v_cvt_pk_bf16_f32 v13, v32, v33
	s_waitcnt lgkmcnt(0)
	v_add_f32_e32 v4, v4, v5
	v_mov_b32_e32 v5, v4
	s_nop 1
	v_permlane32_swap_b32 v4, v5
	global_store_dwordx4 v[18:19], v[10:13], off
	s_nop 1
	v_cvt_pk_bf16_f32 v10, v70, v71
	v_cvt_pk_bf16_f32 v11, v72, v73
	v_cvt_pk_bf16_f32 v12, v78, v79
	v_cvt_pk_bf16_f32 v13, v80, v81
	global_store_dwordx4 v[18:19], v[10:13], off offset:256
	s_and_saveexec_b64 s[28:29], s[36:37]
	s_cbranch_execz .LBB0_526
	v_lshlrev_b64 v[2:3], 5, v[2:3]
	s_waitcnt lgkmcnt(0)
	v_add_f32_e32 v4, v4, v5
	v_lshl_add_u64 v[2:3], s[70:71], 0, v[2:3]
	v_bfe_u32 v5, v4, 16, 1
	v_lshl_add_u64 v[2:3], s[0:1], 1, v[2:3]
	s_lshl_b32 s76, s5, 1
	v_add3_u32 v4, v4, v5, s63
	v_lshl_add_u64 v[2:3], v[2:3], 0, s[76:77]
	global_store_short_d16_hi v[2:3], v4, off
.LBB0_526:
	s_or_b64 exec, exec, s[28:29]
	v_mul_f32_e32 v12, v15, v15
	v_mul_f32_e32 v13, v27, v27
	v_fmac_f32_e32 v12, v14, v14
	v_fmac_f32_e32 v13, v26, v26
	v_fmac_f32_e32 v12, v16, v16
	v_fmac_f32_e32 v13, v28, v28
	v_fmac_f32_e32 v12, v17, v17
	v_fmac_f32_e32 v13, v29, v29
	v_fmac_f32_e32 v12, v6, v6
	v_fmac_f32_e32 v13, v34, v34
	v_fmac_f32_e32 v12, v7, v7
	v_fmac_f32_e32 v13, v35, v35
	v_fmac_f32_e32 v12, v8, v8
	v_fmac_f32_e32 v13, v36, v36
	v_fmac_f32_e32 v12, v9, v9
	v_fmac_f32_e32 v13, v37, v37
	v_add_f32_e32 v12, v12, v13
	v_add_u32_e32 v2, 0xb0, v142
	v_mov_b32_e32 v13, v12
	s_nop 1
	v_permlane16_swap_b32 v12, v13
	v_ashrrev_i32_e32 v3, 31, v2
	s_waitcnt lgkmcnt(0)
	v_lshlrev_b64 v[4:5], 11, v[2:3]
	v_lshl_add_u64 v[4:5], s[92:93], 0, v[4:5]
	v_lshl_add_u64 v[10:11], v[140:141], 1, v[4:5]
	v_cvt_pk_bf16_f32 v4, v14, v15
	v_cvt_pk_bf16_f32 v5, v16, v17
	v_cvt_pk_bf16_f32 v6, v6, v7
	v_cvt_pk_bf16_f32 v7, v8, v9
	global_store_dwordx4 v[10:11], v[4:7], off
	v_cvt_pk_bf16_f32 v8, v34, v35
	v_cvt_pk_bf16_f32 v9, v36, v37
	v_add_f32_e32 v4, v12, v13
	v_mov_b32_e32 v5, v4
	s_nop 1
	v_permlane32_swap_b32 v4, v5
	v_cvt_pk_bf16_f32 v6, v26, v27
	v_cvt_pk_bf16_f32 v7, v28, v29
	global_store_dwordx4 v[10:11], v[6:9], off offset:256
	s_and_saveexec_b64 s[28:29], s[36:37]
	s_cbranch_execz .LBB0_528
	v_lshlrev_b64 v[2:3], 5, v[2:3]
	s_waitcnt lgkmcnt(0)
	v_add_f32_e32 v4, v4, v5
	v_lshl_add_u64 v[2:3], s[70:71], 0, v[2:3]
	v_bfe_u32 v5, v4, 16, 1
	v_lshl_add_u64 v[2:3], s[0:1], 1, v[2:3]
	s_lshl_b32 s76, s5, 1
	v_add3_u32 v4, v4, v5, s63
	v_lshl_add_u64 v[2:3], v[2:3], 0, s[76:77]
	global_store_short_d16_hi v[2:3], v4, off

; DI bf16_t f2bf(float x) { unsigned u = __float_as_uint(x); u += 0x7fffu + ((u >> 16) & 1u); return (bf16_t)(u >> 16); }
; DI unsigned pack2(float lo, float hi) { f32x2_t v = {lo, hi}; return __builtin_bit_cast(unsigned, __builtin_convertvector(v, bf16x2_t)); }
; #define PG8_LAS __attribute__((address_space(3)))
;   DI void operator()(const f32x4 (&acc)[2][2][4][2], const Unit& u, int wr, int wc, int fr, int fq, const PG8_LAS float*) const {
;     const int row0 = u.pm * BM + wr * 64 + fr, col0 = u.pn * BM + wc * 32 + 8 * fq;
; #pragma unroll
;     for (int ai = 0; ai < 2; ++ai)
; #pragma unroll
;       for (int m = 0; m < 4; ++m) { const int row = row0 + ai * HALF + m * 16; bf16_t* rowp = dst + (size_t)row * DM + col0; float ss = 0.f;
; #pragma unroll
;         for (int bj = 0; bj < 2; ++bj) { const f32x4 v0 = acc[ai][bj][m][0] * coef, v1 = acc[ai][bj][m][1] * coef;
;           ss += v0[0] * v0[0] + v0[1] * v0[1] + v0[2] * v0[2] + v0[3] * v0[3] + v1[0] * v1[0] + v1[1] * v1[1] + v1[2] * v1[2] + v1[3] * v1[3];
;           u32x4 w; w.x = pack2(v0[0], v0[1]); w.y = pack2(v0[2], v0[3]); w.z = pack2(v1[0], v1[1]); w.w = pack2(v1[2], v1[3]);
;           *(u32x4*)(rowp + bj * HALF) = w; }
;         ss += __shfl_xor(ss, 16); ss += __shfl_xor(ss, 32);
;         if (fq == 0) ssq[(size_t)row * 16 + u.pn * 4 + wc] = f2bf(ss); }
.Leinit684_skip:
	v_pk_mul_f32 v[126:127], v[126:127], 0.5 op_sel_hi:[1,0]
	v_pk_mul_f32 v[128:129], v[128:129], 0.5 op_sel_hi:[1,0]
	v_mul_f32_e32 v154, v127, v127
	v_fmac_f32_e32 v154, v126, v126
	v_fmac_f32_e32 v154, v128, v128
	v_pk_mul_f32 v[118:119], v[118:119], 0.5 op_sel_hi:[1,0]
	v_pk_mul_f32 v[152:153], v[124:125], 0.5 op_sel_hi:[1,0]
	v_pk_mul_f32 v[124:125], v[122:123], 0.5 op_sel_hi:[1,0]
	v_fmac_f32_e32 v154, v129, v129
	v_cvt_pk_bf16_f32 v123, v128, v129
	v_pk_mul_f32 v[128:129], v[114:115], 0.5 op_sel_hi:[1,0]
	v_mul_f32_e32 v114, v119, v119
	v_pk_mul_f32 v[120:121], v[120:121], 0.5 op_sel_hi:[1,0]
	v_fmac_f32_e32 v114, v118, v118
	v_fmac_f32_e32 v114, v120, v120
	v_fmac_f32_e32 v114, v121, v121
	v_fmac_f32_e32 v154, v124, v124
	v_fmac_f32_e32 v114, v128, v128
	v_xor_b32_e32 v143, 16, v223
	v_fmac_f32_e32 v154, v125, v125
	v_cvt_pk_bf16_f32 v122, v126, v127
	v_pk_mul_f32 v[126:127], v[116:117], 0.5 op_sel_hi:[1,0]
	v_fmac_f32_e32 v114, v129, v129
	v_cmp_lt_i32_e32 vcc, v143, v225
	v_fmac_f32_e32 v154, v152, v152
	v_fmac_f32_e32 v114, v126, v126
	v_cndmask_b32_e32 v143, v223, v143, vcc
	v_fmac_f32_e32 v154, v153, v153
	v_fmac_f32_e32 v114, v127, v127
	v_lshlrev_b32_e32 v149, 2, v143
	v_add_f32_e32 v114, v154, v114
	v_mov_b32_e32 v115, v114
	s_nop 1
	v_permlane16_swap_b32 v114, v115
	v_xor_b32_e32 v143, 32, v223
	v_cmp_lt_i32_e32 vcc, v143, v225
	v_lshl_add_u32 v142, s9, 8, v144
	v_lshl_or_b32 v140, s76, 8, v147
	v_cndmask_b32_e32 v143, v223, v143, vcc
	v_lshlrev_b32_e32 v148, 2, v143
	s_waitcnt lgkmcnt(0)
	v_add_f32_e32 v114, v114, v115
	v_mov_b32_e32 v115, v114
	s_nop 1
	v_permlane32_swap_b32 v114, v115
	v_ashrrev_i32_e32 v143, 31, v142
	v_lshlrev_b64 v[150:151], 11, v[142:143]
	v_ashrrev_i32_e32 v141, 31, v140
	s_lshl_b32 s28, s76, 2
	v_lshl_add_u64 v[150:151], s[26:27], 0, v[150:151]
	s_ashr_i32 s29, s28, 31
	v_lshl_add_u64 v[150:151], v[140:141], 1, v[150:151]
	v_cvt_pk_bf16_f32 v124, v124, v125
	v_cvt_pk_bf16_f32 v125, v152, v153
	v_cvt_pk_bf16_f32 v116, v118, v119
	v_cvt_pk_bf16_f32 v117, v120, v121
	v_cvt_pk_bf16_f32 v118, v128, v129
	v_cvt_pk_bf16_f32 v119, v126, v127
	global_store_dwordx4 v[150:151], v[122:125], off
	global_store_dwordx4 v[150:151], v[116:119], off offset:256
	s_and_saveexec_b64 s[30:31], s[36:37]
	s_cbranch_execz .LBB0_687
	s_waitcnt lgkmcnt(0)
	v_add_f32_e32 v114, v114, v115
	v_bfe_u32 v115, v114, 16, 1
	v_add3_u32 v116, v114, v115, s63
	v_lshlrev_b64 v[114:115], 5, v[142:143]
	v_lshl_add_u64 v[114:115], s[84:85], 0, v[114:115]
	v_lshl_add_u64 v[114:115], s[28:29], 1, v[114:115]
	s_lshl_b32 s76, s7, 1
	v_lshl_add_u64 v[114:115], v[114:115], 0, s[76:77]
	global_store_short_d16_hi v[114:115], v116, off
.LBB0_687:
	s_or_b64 exec, exec, s[30:31]
	v_pk_mul_f32 v[110:111], v[110:111], 0.5 op_sel_hi:[1,0]
	v_pk_mul_f32 v[112:113], v[112:113], 0.5 op_sel_hi:[1,0]
	v_mul_f32_e32 v120, v111, v111
	v_fmac_f32_e32 v120, v110, v110
	v_fmac_f32_e32 v120, v112, v112
	v_pk_mul_f32 v[102:103], v[102:103], 0.5 op_sel_hi:[1,0]
	v_pk_mul_f32 v[118:119], v[108:109], 0.5 op_sel_hi:[1,0]
	v_pk_mul_f32 v[108:109], v[106:107], 0.5 op_sel_hi:[1,0]
	v_fmac_f32_e32 v120, v113, v113
	v_cvt_pk_bf16_f32 v107, v112, v113
	v_pk_mul_f32 v[112:113], v[98:99], 0.5 op_sel_hi:[1,0]
	v_mul_f32_e32 v98, v103, v103
	v_pk_mul_f32 v[104:105], v[104:105], 0.5 op_sel_hi:[1,0]
	v_fmac_f32_e32 v98, v102, v102
	v_fmac_f32_e32 v98, v104, v104
	v_fmac_f32_e32 v98, v105, v105
	v_fmac_f32_e32 v120, v108, v108
	v_fmac_f32_e32 v98, v112, v112
	v_fmac_f32_e32 v120, v109, v109
	v_cvt_pk_bf16_f32 v106, v110, v111
	v_pk_mul_f32 v[110:111], v[100:101], 0.5 op_sel_hi:[1,0]
	v_fmac_f32_e32 v98, v113, v113
	v_fmac_f32_e32 v120, v118, v118
	v_fmac_f32_e32 v98, v110, v110
	v_fmac_f32_e32 v120, v119, v119
	v_fmac_f32_e32 v98, v111, v111
	v_add_f32_e32 v98, v120, v98
	v_mov_b32_e32 v99, v98
	s_nop 1
	v_permlane16_swap_b32 v98, v99
	v_or_b32_e32 v114, 16, v142
	s_waitcnt lgkmcnt(0)
	v_ashrrev_i32_e32 v115, 31, v114
	v_lshlrev_b64 v[116:117], 11, v[114:115]
	v_lshl_add_u64 v[116:117], s[26:27], 0, v[116:117]
	v_add_f32_e32 v98, v98, v99
	v_mov_b32_e32 v99, v98
	s_nop 1
	v_permlane32_swap_b32 v98, v99
	v_lshl_add_u64 v[116:117], v[140:141], 1, v[116:117]
	v_cvt_pk_bf16_f32 v108, v108, v109
	v_cvt_pk_bf16_f32 v109, v118, v119
	v_cvt_pk_bf16_f32 v100, v102, v103
	v_cvt_pk_bf16_f32 v101, v104, v105
	v_cvt_pk_bf16_f32 v102, v112, v113
	v_cvt_pk_bf16_f32 v103, v110, v111
	global_store_dwordx4 v[116:117], v[106:109], off
	global_store_dwordx4 v[116:117], v[100:103], off offset:256
	s_and_saveexec_b64 s[30:31], s[36:37]
	s_cbranch_execz .LBB0_689
	s_waitcnt lgkmcnt(0)
	v_add_f32_e32 v98, v98, v99
	v_bfe_u32 v99, v98, 16, 1
	v_add3_u32 v100, v98, v99, s63
	v_lshlrev_b64 v[98:99], 5, v[114:115]
	v_lshl_add_u64 v[98:99], s[84:85], 0, v[98:99]
	v_lshl_add_u64 v[98:99], s[28:29], 1, v[98:99]
	s_lshl_b32 s76, s7, 1
	v_lshl_add_u64 v[98:99], v[98:99], 0, s[76:77]
	global_store_short_d16_hi v[98:99], v100, off
; DI bf16_t f2bf(float x) { unsigned u = __float_as_uint(x); u += 0x7fffu + ((u >> 16) & 1u); return (bf16_t)(u >> 16); }
; DI unsigned pack2(float lo, float hi) { f32x2_t v = {lo, hi}; return __builtin_bit_cast(unsigned, __builtin_convertvector(v, bf16x2_t)); }
;   DI void operator()(const f32x4 (&acc)[2][2][4][2], const Unit& u, int wr, int wc, int fr, int fq, const PG8_LAS float*) const {
;     ...
;       for (int m = 0; m < 4; ++m) { const int row = row0 + ai * HALF + m * 16; bf16_t* rowp = dst + (size_t)row * DM + col0; float ss = 0.f;
; #pragma unroll
;         for (int bj = 0; bj < 2; ++bj) { const f32x4 v0 = acc[ai][bj][m][0] * coef, v1 = acc[ai][bj][m][1] * coef;
;           ss += v0[0] * v0[0] + v0[1] * v0[1] + v0[2] * v0[2] + v0[3] * v0[3] + v1[0] * v1[0] + v1[1] * v1[1] + v1[2] * v1[2] + v1[3] * v1[3];
;           u32x4 w; w.x = pack2(v0[0], v0[1]); w.y = pack2(v0[2], v0[3]); w.z = pack2(v1[0], v1[1]); w.w = pack2(v1[2], v1[3]);
;           *(u32x4*)(rowp + bj * HALF) = w; }
;         ss += __shfl_xor(ss, 16); ss += __shfl_xor(ss, 32);
;         if (fq == 0) ssq[(size_t)row * 16 + u.pn * 4 + wc] = f2bf(ss); }
.LBB0_689:
	s_or_b64 exec, exec, s[30:31]
	v_pk_mul_f32 v[94:95], v[94:95], 0.5 op_sel_hi:[1,0]
	v_pk_mul_f32 v[96:97], v[96:97], 0.5 op_sel_hi:[1,0]
	v_mul_f32_e32 v104, v95, v95
	v_fmac_f32_e32 v104, v94, v94
	v_fmac_f32_e32 v104, v96, v96
	v_pk_mul_f32 v[86:87], v[86:87], 0.5 op_sel_hi:[1,0]
	v_pk_mul_f32 v[102:103], v[92:93], 0.5 op_sel_hi:[1,0]
	v_pk_mul_f32 v[92:93], v[90:91], 0.5 op_sel_hi:[1,0]
	v_fmac_f32_e32 v104, v97, v97
	v_cvt_pk_bf16_f32 v91, v96, v97
	v_pk_mul_f32 v[96:97], v[82:83], 0.5 op_sel_hi:[1,0]
	v_mul_f32_e32 v82, v87, v87
	v_pk_mul_f32 v[88:89], v[88:89], 0.5 op_sel_hi:[1,0]
	v_fmac_f32_e32 v82, v86, v86
	v_fmac_f32_e32 v82, v88, v88
	v_fmac_f32_e32 v82, v89, v89
	v_fmac_f32_e32 v104, v92, v92
	v_fmac_f32_e32 v82, v96, v96
	v_fmac_f32_e32 v104, v93, v93
	v_cvt_pk_bf16_f32 v90, v94, v95
	v_pk_mul_f32 v[94:95], v[84:85], 0.5 op_sel_hi:[1,0]
	v_fmac_f32_e32 v82, v97, v97
	v_fmac_f32_e32 v104, v102, v102
	v_fmac_f32_e32 v82, v94, v94
	v_fmac_f32_e32 v104, v103, v103
	v_fmac_f32_e32 v82, v95, v95
	v_add_f32_e32 v82, v104, v82
	v_mov_b32_e32 v83, v82
	s_nop 1
	v_permlane16_swap_b32 v82, v83
	v_or_b32_e32 v98, 32, v142
	s_waitcnt lgkmcnt(0)
	v_ashrrev_i32_e32 v99, 31, v98
	v_lshlrev_b64 v[100:101], 11, v[98:99]
	v_lshl_add_u64 v[100:101], s[26:27], 0, v[100:101]
	v_add_f32_e32 v82, v82, v83
	v_mov_b32_e32 v83, v82
	s_nop 1
	v_permlane32_swap_b32 v82, v83
	v_lshl_add_u64 v[100:101], v[140:141], 1, v[100:101]
	v_cvt_pk_bf16_f32 v92, v92, v93
	v_cvt_pk_bf16_f32 v93, v102, v103
	v_cvt_pk_bf16_f32 v84, v86, v87
	v_cvt_pk_bf16_f32 v85, v88, v89
	v_cvt_pk_bf16_f32 v86, v96, v97
	v_cvt_pk_bf16_f32 v87, v94, v95
	global_store_dwordx4 v[100:101], v[90:93], off
	global_store_dwordx4 v[100:101], v[84:87], off offset:256
	s_and_saveexec_b64 s[30:31], s[36:37]
	s_cbranch_execz .LBB0_691
	s_waitcnt lgkmcnt(0)
	v_add_f32_e32 v82, v82, v83
	v_bfe_u32 v83, v82, 16, 1
	v_add3_u32 v84, v82, v83, s63
	v_lshlrev_b64 v[82:83], 5, v[98:99]
	v_lshl_add_u64 v[82:83], s[84:85], 0, v[82:83]
	v_lshl_add_u64 v[82:83], s[28:29], 1, v[82:83]
	s_lshl_b32 s76, s7, 1
	v_lshl_add_u64 v[82:83], v[82:83], 0, s[76:77]
	global_store_short_d16_hi v[82:83], v84, off
.LBB0_691:
	s_or_b64 exec, exec, s[30:31]
	v_pk_mul_f32 v[78:79], v[78:79], 0.5 op_sel_hi:[1,0]
	v_pk_mul_f32 v[80:81], v[80:81], 0.5 op_sel_hi:[1,0]
	v_mul_f32_e32 v88, v79, v79
	v_fmac_f32_e32 v88, v78, v78
	v_fmac_f32_e32 v88, v80, v80
	v_pk_mul_f32 v[70:71], v[70:71], 0.5 op_sel_hi:[1,0]
	v_pk_mul_f32 v[86:87], v[76:77], 0.5 op_sel_hi:[1,0]
	v_pk_mul_f32 v[76:77], v[74:75], 0.5 op_sel_hi:[1,0]
	v_fmac_f32_e32 v88, v81, v81
	v_cvt_pk_bf16_f32 v75, v80, v81
	v_pk_mul_f32 v[80:81], v[66:67], 0.5 op_sel_hi:[1,0]
	v_mul_f32_e32 v66, v71, v71
	v_pk_mul_f32 v[72:73], v[72:73], 0.5 op_sel_hi:[1,0]
	v_fmac_f32_e32 v66, v70, v70
	v_fmac_f32_e32 v66, v72, v72
	v_fmac_f32_e32 v66, v73, v73
	v_fmac_f32_e32 v88, v76, v76
	v_fmac_f32_e32 v66, v80, v80
	v_fmac_f32_e32 v88, v77, v77
	v_cvt_pk_bf16_f32 v74, v78, v79
	v_pk_mul_f32 v[78:79], v[68:69], 0.5 op_sel_hi:[1,0]
	v_fmac_f32_e32 v66, v81, v81
	v_fmac_f32_e32 v88, v86, v86
	v_fmac_f32_e32 v66, v78, v78
	v_fmac_f32_e32 v88, v87, v87
	v_fmac_f32_e32 v66, v79, v79
	v_add_f32_e32 v66, v88, v66
	v_mov_b32_e32 v67, v66
	s_nop 1
	v_permlane16_swap_b32 v66, v67
	v_or_b32_e32 v82, 48, v142
	s_waitcnt lgkmcnt(0)
	v_ashrrev_i32_e32 v83, 31, v82
	v_lshlrev_b64 v[84:85], 11, v[82:83]
	v_lshl_add_u64 v[84:85], s[26:27], 0, v[84:85]
	v_add_f32_e32 v66, v66, v67
	v_mov_b32_e32 v67, v66
	s_nop 1
	v_permlane32_swap_b32 v66, v67
	v_lshl_add_u64 v[84:85], v[140:141], 1, v[84:85]
	v_cvt_pk_bf16_f32 v76, v76, v77
	v_cvt_pk_bf16_f32 v77, v86, v87
	v_cvt_pk_bf16_f32 v68, v70, v71
	v_cvt_pk_bf16_f32 v69, v72, v73
	v_cvt_pk_bf16_f32 v70, v80, v81
	v_cvt_pk_bf16_f32 v71, v78, v79
	global_store_dwordx4 v[84:85], v[74:77], off
	global_store_dwordx4 v[84:85], v[68:71], off offset:256
	s_and_saveexec_b64 s[30:31], s[36:37]
	s_cbranch_execz .LBB0_693
	s_waitcnt lgkmcnt(0)
	v_add_f32_e32 v66, v66, v67
	v_bfe_u32 v67, v66, 16, 1
	v_add3_u32 v68, v66, v67, s63
	v_lshlrev_b64 v[66:67], 5, v[82:83]
	v_lshl_add_u64 v[66:67], s[84:85], 0, v[66:67]
	v_lshl_add_u64 v[66:67], s[28:29], 1, v[66:67]
	s_lshl_b32 s76, s7, 1
	v_lshl_add_u64 v[66:67], v[66:67], 0, s[76:77]
	global_store_short_d16_hi v[66:67], v68, off
.LBB0_693:
	s_or_b64 exec, exec, s[30:31]
	v_pk_mul_f32 v[62:63], v[62:63], 0.5 op_sel_hi:[1,0]
	v_pk_mul_f32 v[64:65], v[64:65], 0.5 op_sel_hi:[1,0]
	v_mul_f32_e32 v72, v63, v63
	v_fmac_f32_e32 v72, v62, v62
	v_fmac_f32_e32 v72, v64, v64
	v_pk_mul_f32 v[54:55], v[54:55], 0.5 op_sel_hi:[1,0]
	v_pk_mul_f32 v[70:71], v[60:61], 0.5 op_sel_hi:[1,0]
	v_pk_mul_f32 v[60:61], v[58:59], 0.5 op_sel_hi:[1,0]
	v_fmac_f32_e32 v72, v65, v65
	v_cvt_pk_bf16_f32 v59, v64, v65
	v_pk_mul_f32 v[64:65], v[50:51], 0.5 op_sel_hi:[1,0]
	v_mul_f32_e32 v50, v55, v55
	v_pk_mul_f32 v[56:57], v[56:57], 0.5 op_sel_hi:[1,0]
	v_fmac_f32_e32 v50, v54, v54
	v_fmac_f32_e32 v50, v56, v56
	v_fmac_f32_e32 v50, v57, v57
	v_fmac_f32_e32 v72, v60, v60
	v_fmac_f32_e32 v50, v64, v64
	v_fmac_f32_e32 v72, v61, v61
	v_cvt_pk_bf16_f32 v58, v62, v63
	v_pk_mul_f32 v[62:63], v[52:53], 0.5 op_sel_hi:[1,0]
	v_fmac_f32_e32 v50, v65, v65
	v_fmac_f32_e32 v72, v70, v70
	v_fmac_f32_e32 v50, v62, v62
	v_fmac_f32_e32 v72, v71, v71
	v_fmac_f32_e32 v50, v63, v63
	v_add_f32_e32 v50, v72, v50
	v_mov_b32_e32 v51, v50
	s_nop 1
	v_permlane16_swap_b32 v50, v51
	v_add_u32_e32 v66, 0x80, v142
	s_waitcnt lgkmcnt(0)
	v_ashrrev_i32_e32 v67, 31, v66
	v_lshlrev_b64 v[68:69], 11, v[66:67]
	v_lshl_add_u64 v[68:69], s[26:27], 0, v[68:69]
	v_add_f32_e32 v50, v50, v51
	v_mov_b32_e32 v51, v50
	s_nop 1
	v_permlane32_swap_b32 v50, v51
	v_lshl_add_u64 v[68:69], v[140:141], 1, v[68:69]
	v_cvt_pk_bf16_f32 v60, v60, v61
	v_cvt_pk_bf16_f32 v61, v70, v71
	v_cvt_pk_bf16_f32 v52, v54, v55
	v_cvt_pk_bf16_f32 v53, v56, v57
	v_cvt_pk_bf16_f32 v54, v64, v65
	v_cvt_pk_bf16_f32 v55, v62, v63
	global_store_dwordx4 v[68:69], v[58:61], off
	global_store_dwordx4 v[68:69], v[52:55], off offset:256
	s_and_saveexec_b64 s[30:31], s[36:37]
	s_cbranch_execz .LBB0_695
	s_waitcnt lgkmcnt(0)
	v_add_f32_e32 v50, v50, v51
	v_bfe_u32 v51, v50, 16, 1
	v_add3_u32 v52, v50, v51, s63
	v_lshlrev_b64 v[50:51], 5, v[66:67]
	v_lshl_add_u64 v[50:51], s[84:85], 0, v[50:51]
	v_lshl_add_u64 v[50:51], s[28:29], 1, v[50:51]
	s_lshl_b32 s76, s7, 1
	v_lshl_add_u64 v[50:51], v[50:51], 0, s[76:77]
	global_store_short_d16_hi v[50:51], v52, off
; DI bf16_t f2bf(float x) { unsigned u = __float_as_uint(x); u += 0x7fffu + ((u >> 16) & 1u); return (bf16_t)(u >> 16); }
; DI unsigned pack2(float lo, float hi) { f32x2_t v = {lo, hi}; return __builtin_bit_cast(unsigned, __builtin_convertvector(v, bf16x2_t)); }
;   DI void operator()(const f32x4 (&acc)[2][2][4][2], const Unit& u, int wr, int wc, int fr, int fq, const PG8_LAS float*) const {
;     ...
;       for (int m = 0; m < 4; ++m) { const int row = row0 + ai * HALF + m * 16; bf16_t* rowp = dst + (size_t)row * DM + col0; float ss = 0.f;
; #pragma unroll
;         for (int bj = 0; bj < 2; ++bj) { const f32x4 v0 = acc[ai][bj][m][0] * coef, v1 = acc[ai][bj][m][1] * coef;
;           ss += v0[0] * v0[0] + v0[1] * v0[1] + v0[2] * v0[2] + v0[3] * v0[3] + v1[0] * v1[0] + v1[1] * v1[1] + v1[2] * v1[2] + v1[3] * v1[3];
;           u32x4 w; w.x = pack2(v0[0], v0[1]); w.y = pack2(v0[2], v0[3]); w.z = pack2(v1[0], v1[1]); w.w = pack2(v1[2], v1[3]);
;           *(u32x4*)(rowp + bj * HALF) = w; }
;         ss += __shfl_xor(ss, 16); ss += __shfl_xor(ss, 32);
;         if (fq == 0) ssq[(size_t)row * 16 + u.pn * 4 + wc] = f2bf(ss); }
.LBB0_695:
	s_or_b64 exec, exec, s[30:31]
	v_pk_mul_f32 v[46:47], v[46:47], 0.5 op_sel_hi:[1,0]
	v_pk_mul_f32 v[48:49], v[48:49], 0.5 op_sel_hi:[1,0]
	v_mul_f32_e32 v56, v47, v47
	v_fmac_f32_e32 v56, v46, v46
	v_fmac_f32_e32 v56, v48, v48
	v_pk_mul_f32 v[38:39], v[38:39], 0.5 op_sel_hi:[1,0]
	v_pk_mul_f32 v[54:55], v[44:45], 0.5 op_sel_hi:[1,0]
	v_pk_mul_f32 v[44:45], v[42:43], 0.5 op_sel_hi:[1,0]
	v_fmac_f32_e32 v56, v49, v49
	v_cvt_pk_bf16_f32 v43, v48, v49
	v_pk_mul_f32 v[48:49], v[34:35], 0.5 op_sel_hi:[1,0]
	v_mul_f32_e32 v34, v39, v39
	v_pk_mul_f32 v[40:41], v[40:41], 0.5 op_sel_hi:[1,0]
	v_fmac_f32_e32 v34, v38, v38
	v_fmac_f32_e32 v34, v40, v40
	v_fmac_f32_e32 v34, v41, v41
	v_fmac_f32_e32 v56, v44, v44
	v_fmac_f32_e32 v34, v48, v48
	v_fmac_f32_e32 v56, v45, v45
	v_cvt_pk_bf16_f32 v42, v46, v47
	v_pk_mul_f32 v[46:47], v[36:37], 0.5 op_sel_hi:[1,0]
	v_fmac_f32_e32 v34, v49, v49
	v_fmac_f32_e32 v56, v54, v54
	v_fmac_f32_e32 v34, v46, v46
	v_fmac_f32_e32 v56, v55, v55
	v_fmac_f32_e32 v34, v47, v47
	v_add_f32_e32 v34, v56, v34
	v_mov_b32_e32 v35, v34
	s_nop 1
	v_permlane16_swap_b32 v34, v35
	v_add_u32_e32 v50, 0x90, v142
	s_waitcnt lgkmcnt(0)
	v_ashrrev_i32_e32 v51, 31, v50
	v_lshlrev_b64 v[52:53], 11, v[50:51]
	v_lshl_add_u64 v[52:53], s[26:27], 0, v[52:53]
	v_add_f32_e32 v34, v34, v35
	v_mov_b32_e32 v35, v34
	s_nop 1
	v_permlane32_swap_b32 v34, v35
	v_lshl_add_u64 v[52:53], v[140:141], 1, v[52:53]
	v_cvt_pk_bf16_f32 v44, v44, v45
	v_cvt_pk_bf16_f32 v45, v54, v55
	v_cvt_pk_bf16_f32 v36, v38, v39
	v_cvt_pk_bf16_f32 v37, v40, v41
	v_cvt_pk_bf16_f32 v38, v48, v49
	v_cvt_pk_bf16_f32 v39, v46, v47
	global_store_dwordx4 v[52:53], v[42:45], off
	global_store_dwordx4 v[52:53], v[36:39], off offset:256
	s_and_saveexec_b64 s[30:31], s[36:37]
	s_cbranch_execz .LBB0_697
	s_waitcnt lgkmcnt(0)
	v_add_f32_e32 v34, v34, v35
	v_bfe_u32 v35, v34, 16, 1
	v_add3_u32 v36, v34, v35, s63
	v_lshlrev_b64 v[34:35], 5, v[50:51]
	v_lshl_add_u64 v[34:35], s[84:85], 0, v[34:35]
	v_lshl_add_u64 v[34:35], s[28:29], 1, v[34:35]
	s_lshl_b32 s76, s7, 1
	v_lshl_add_u64 v[34:35], v[34:35], 0, s[76:77]
	global_store_short_d16_hi v[34:35], v36, off
.LBB0_697:
	s_or_b64 exec, exec, s[30:31]
	v_pk_mul_f32 v[30:31], v[30:31], 0.5 op_sel_hi:[1,0]
	v_pk_mul_f32 v[32:33], v[32:33], 0.5 op_sel_hi:[1,0]
	v_mul_f32_e32 v40, v31, v31
	v_fmac_f32_e32 v40, v30, v30
	v_fmac_f32_e32 v40, v32, v32
	v_pk_mul_f32 v[22:23], v[22:23], 0.5 op_sel_hi:[1,0]
	v_pk_mul_f32 v[38:39], v[28:29], 0.5 op_sel_hi:[1,0]
	v_pk_mul_f32 v[28:29], v[26:27], 0.5 op_sel_hi:[1,0]
	v_fmac_f32_e32 v40, v33, v33
	v_cvt_pk_bf16_f32 v27, v32, v33
	v_pk_mul_f32 v[32:33], v[18:19], 0.5 op_sel_hi:[1,0]
	v_mul_f32_e32 v18, v23, v23
	v_pk_mul_f32 v[24:25], v[24:25], 0.5 op_sel_hi:[1,0]
	v_fmac_f32_e32 v18, v22, v22
	v_fmac_f32_e32 v18, v24, v24
	v_fmac_f32_e32 v18, v25, v25
	v_fmac_f32_e32 v40, v28, v28
	v_fmac_f32_e32 v18, v32, v32
	v_fmac_f32_e32 v40, v29, v29
	v_cvt_pk_bf16_f32 v26, v30, v31
	v_pk_mul_f32 v[30:31], v[20:21], 0.5 op_sel_hi:[1,0]
	v_fmac_f32_e32 v18, v33, v33
	v_fmac_f32_e32 v40, v38, v38
	v_fmac_f32_e32 v18, v30, v30
	v_fmac_f32_e32 v40, v39, v39
	v_fmac_f32_e32 v18, v31, v31
	v_add_f32_e32 v18, v40, v18
	v_mov_b32_e32 v19, v18
	s_nop 1
	v_permlane16_swap_b32 v18, v19
	v_add_u32_e32 v34, 0xa0, v142
	s_waitcnt lgkmcnt(0)
	v_ashrrev_i32_e32 v35, 31, v34
	v_lshlrev_b64 v[36:37], 11, v[34:35]
	v_lshl_add_u64 v[36:37], s[26:27], 0, v[36:37]
	v_add_f32_e32 v18, v18, v19
	v_mov_b32_e32 v19, v18
	s_nop 1
	v_permlane32_swap_b32 v18, v19
	v_lshl_add_u64 v[36:37], v[140:141], 1, v[36:37]
	v_cvt_pk_bf16_f32 v28, v28, v29
	v_cvt_pk_bf16_f32 v29, v38, v39
	v_cvt_pk_bf16_f32 v20, v22, v23
	v_cvt_pk_bf16_f32 v21, v24, v25
	v_cvt_pk_bf16_f32 v22, v32, v33
	v_cvt_pk_bf16_f32 v23, v30, v31
	global_store_dwordx4 v[36:37], v[26:29], off
	global_store_dwordx4 v[36:37], v[20:23], off offset:256
	s_and_saveexec_b64 s[30:31], s[36:37]
	s_cbranch_execz .LBB0_699
	s_waitcnt lgkmcnt(0)
	v_add_f32_e32 v18, v18, v19
	v_bfe_u32 v19, v18, 16, 1
	v_add3_u32 v20, v18, v19, s63
	v_lshlrev_b64 v[18:19], 5, v[34:35]
	v_lshl_add_u64 v[18:19], s[84:85], 0, v[18:19]
	v_lshl_add_u64 v[18:19], s[28:29], 1, v[18:19]
	s_lshl_b32 s76, s7, 1
	v_lshl_add_u64 v[18:19], v[18:19], 0, s[76:77]
	global_store_short_d16_hi v[18:19], v20, off
.LBB0_699:
	s_or_b64 exec, exec, s[30:31]
	v_pk_mul_f32 v[14:15], v[14:15], 0.5 op_sel_hi:[1,0]
	v_pk_mul_f32 v[16:17], v[16:17], 0.5 op_sel_hi:[1,0]
	v_mul_f32_e32 v24, v15, v15
	v_fmac_f32_e32 v24, v14, v14
	v_fmac_f32_e32 v24, v16, v16
	v_pk_mul_f32 v[6:7], v[6:7], 0.5 op_sel_hi:[1,0]
	v_pk_mul_f32 v[22:23], v[12:13], 0.5 op_sel_hi:[1,0]
	v_pk_mul_f32 v[12:13], v[10:11], 0.5 op_sel_hi:[1,0]
	v_fmac_f32_e32 v24, v17, v17
	v_cvt_pk_bf16_f32 v11, v16, v17
	v_pk_mul_f32 v[16:17], v[2:3], 0.5 op_sel_hi:[1,0]
	v_mul_f32_e32 v2, v7, v7
	v_pk_mul_f32 v[8:9], v[8:9], 0.5 op_sel_hi:[1,0]
	v_fmac_f32_e32 v2, v6, v6
	v_fmac_f32_e32 v2, v8, v8
	v_fmac_f32_e32 v2, v9, v9
	v_fmac_f32_e32 v24, v12, v12
	v_fmac_f32_e32 v2, v16, v16
	v_fmac_f32_e32 v24, v13, v13
	v_cvt_pk_bf16_f32 v10, v14, v15
	v_pk_mul_f32 v[14:15], v[4:5], 0.5 op_sel_hi:[1,0]
	v_fmac_f32_e32 v2, v17, v17
	v_fmac_f32_e32 v24, v22, v22
	v_fmac_f32_e32 v2, v14, v14
	v_fmac_f32_e32 v24, v23, v23
	v_fmac_f32_e32 v2, v15, v15
	v_add_f32_e32 v2, v24, v2
	v_mov_b32_e32 v3, v2
	s_nop 1
	v_permlane16_swap_b32 v2, v3
	v_add_u32_e32 v18, 0xb0, v142
	s_waitcnt lgkmcnt(0)
	v_ashrrev_i32_e32 v19, 31, v18
	v_lshlrev_b64 v[20:21], 11, v[18:19]
	v_lshl_add_u64 v[20:21], s[26:27], 0, v[20:21]
	v_add_f32_e32 v2, v2, v3
	v_mov_b32_e32 v3, v2
	s_nop 1
	v_permlane32_swap_b32 v2, v3
	v_lshl_add_u64 v[20:21], v[140:141], 1, v[20:21]
	v_cvt_pk_bf16_f32 v12, v12, v13
	v_cvt_pk_bf16_f32 v13, v22, v23
	v_cvt_pk_bf16_f32 v4, v6, v7
	v_cvt_pk_bf16_f32 v5, v8, v9
	v_cvt_pk_bf16_f32 v6, v16, v17
	v_cvt_pk_bf16_f32 v7, v14, v15
	global_store_dwordx4 v[20:21], v[10:13], off
	global_store_dwordx4 v[20:21], v[4:7], off offset:256
	s_and_saveexec_b64 s[30:31], s[36:37]
	s_cbranch_execz .LBB0_701
	s_waitcnt lgkmcnt(0)
	v_add_f32_e32 v2, v2, v3
	v_bfe_u32 v3, v2, 16, 1
	v_add3_u32 v4, v2, v3, s63
	v_lshlrev_b64 v[2:3], 5, v[18:19]
	v_lshl_add_u64 v[2:3], s[84:85], 0, v[2:3]
	v_lshl_add_u64 v[2:3], s[28:29], 1, v[2:3]
	s_lshl_b32 s76, s7, 1
	v_lshl_add_u64 v[2:3], v[2:3], 0, s[76:77]
	global_store_short_d16_hi v[2:3], v4, off
